# v11 + nt on P1 input-row loads and the conditioning weight (w_ada) loads
# baseline (speedup 1.0000x reference)
.LBB0_12:
	v_add_co_u32_e32 v30, vcc, s8, v8
	global_load_dwordx2 v[112:113], v[8:9], off nt
	s_nop 0
	v_addc_co_u32_e32 v31, vcc, -1, v9, vcc
	v_add_co_u32_e32 v32, vcc, s9, v8
	s_add_i32 s25, s24, 0x10000
	s_nop 0
	v_addc_co_u32_e32 v33, vcc, -1, v9, vcc
	v_add_co_u32_e32 v34, vcc, s13, v8
	s_add_i32 s26, s24, 0x12000
	s_nop 0
	v_addc_co_u32_e32 v35, vcc, -1, v9, vcc
	v_add_co_u32_e32 v36, vcc, s14, v8
	s_add_i32 s27, s24, 0x10010
	s_nop 0
	v_addc_co_u32_e32 v37, vcc, -1, v9, vcc
	v_add_co_u32_e32 v40, vcc, s15, v8
	s_add_i32 s28, s24, 0x12010
	s_nop 0
	v_addc_co_u32_e32 v41, vcc, -1, v9, vcc
	v_add_co_u32_e32 v42, vcc, s18, v8
	v_mov_b32_e32 v92, s24
	s_nop 0
	v_addc_co_u32_e32 v43, vcc, -1, v9, vcc
	v_add_co_u32_e32 v44, vcc, s19, v8
	v_mov_b32_e32 v96, s25
	s_nop 0
	v_addc_co_u32_e32 v45, vcc, -1, v9, vcc
	global_load_dwordx2 v[114:115], v[32:33], off nt
	global_load_dwordx2 v[116:117], v[42:43], off nt
	global_load_dwordx2 v[118:119], v[34:35], off nt
	global_load_dwordx2 v[120:121], v[36:37], off nt
	global_load_dwordx2 v[122:123], v[30:31], off nt
	global_load_dwordx2 v[124:125], v[44:45], off nt
	global_load_dwordx2 v[126:127], v[40:41], off nt
	v_mov_b32_e32 v100, s26
	v_mov_b32_e32 v104, s27
	v_mov_b32_e32 v108, s28
	ds_read_b128 v[30:33], v92
	ds_read_b128 v[34:37], v92 offset:16
	ds_read_b128 v[40:43], v92 offset:8192
	ds_read_b128 v[44:47], v92 offset:8208
	ds_read_b128 v[48:51], v92 offset:16384
	ds_read_b128 v[52:55], v92 offset:16400
	ds_read_b128 v[56:59], v92 offset:24576
	ds_read_b128 v[60:63], v92 offset:24592
	ds_read_b128 v[64:67], v92 offset:32768
	ds_read_b128 v[68:71], v92 offset:32784
	ds_read_b128 v[72:75], v92 offset:40960
	ds_read_b128 v[76:79], v92 offset:40976
	ds_read_b128 v[80:83], v92 offset:49152
	ds_read_b128 v[84:87], v92 offset:49168
	ds_read_b128 v[88:91], v92 offset:57344
	ds_read_b128 v[92:95], v92 offset:57360
	ds_read_b128 v[96:99], v96
	ds_read_b128 v[100:103], v100
	ds_read_b128 v[104:107], v104
	ds_read_b128 v[108:111], v108
	s_waitcnt lgkmcnt(14)
	v_mov_b32_e32 v128, v33
	v_mov_b32_e32 v130, v43
	v_mov_b32_e32 v132, v51
	s_waitcnt lgkmcnt(13)
	v_mov_b32_e32 v134, v59
	s_waitcnt lgkmcnt(11)
	v_mov_b32_e32 v136, v67
	s_waitcnt lgkmcnt(9)
	v_mov_b32_e32 v138, v75
	s_waitcnt lgkmcnt(7)
	v_mov_b32_e32 v140, v83
	s_waitcnt lgkmcnt(5)
	v_mov_b32_e32 v142, v91
	s_waitcnt lgkmcnt(3)
	v_mov_b32_e32 v160, v99
	s_waitcnt lgkmcnt(2)
	v_mov_b32_e32 v162, v103
	v_mov_b32_e32 v144, v37
	v_mov_b32_e32 v146, v47
	v_mov_b32_e32 v148, v55
	v_mov_b32_e32 v150, v63
	v_mov_b32_e32 v152, v71
	v_mov_b32_e32 v154, v79
	v_mov_b32_e32 v156, v87
	v_mov_b32_e32 v158, v95
	s_waitcnt lgkmcnt(1)
	v_mov_b32_e32 v164, v107
	s_waitcnt lgkmcnt(0)
	v_mov_b32_e32 v166, v111
	s_add_i32 s23, s23, 8
	s_add_i32 s24, s24, 32
	v_lshl_add_u64 v[8:9], v[8:9], 0, s[0:1]
	s_cmpk_gt_u32 s23, 0xfb
	s_waitcnt vmcnt(6)
	v_pk_mul_f32 v[168:169], v[114:115], v[30:31] op_sel:[0,1]
	v_pk_mul_f32 v[170:171], v[114:115], v[40:41] op_sel:[0,1]
	v_pk_mul_f32 v[172:173], v[114:115], v[48:49] op_sel:[0,1]
	v_pk_mul_f32 v[174:175], v[114:115], v[56:57] op_sel:[0,1]
	v_pk_mul_f32 v[176:177], v[114:115], v[64:65] op_sel:[0,1]
	v_pk_mul_f32 v[178:179], v[114:115], v[72:73] op_sel:[0,1]
	v_pk_mul_f32 v[180:181], v[114:115], v[80:81] op_sel:[0,1]
	v_pk_mul_f32 v[182:183], v[114:115], v[88:89] op_sel:[0,1]
	v_pk_mul_f32 v[184:185], v[114:115], v[96:97] op_sel:[0,1]
	v_pk_mul_f32 v[114:115], v[114:115], v[100:101] op_sel:[0,1]
	s_waitcnt vmcnt(5)
	v_pk_mul_f32 v[186:187], v[116:117], v[34:35] op_sel:[0,1]
	v_pk_mul_f32 v[188:189], v[116:117], v[44:45] op_sel:[0,1]
	v_pk_mul_f32 v[190:191], v[116:117], v[52:53] op_sel:[0,1]
	v_pk_mul_f32 v[192:193], v[116:117], v[60:61] op_sel:[0,1]
	v_pk_mul_f32 v[194:195], v[116:117], v[68:69] op_sel:[0,1]
	v_pk_mul_f32 v[196:197], v[116:117], v[76:77] op_sel:[0,1]
	v_pk_mul_f32 v[198:199], v[116:117], v[84:85] op_sel:[0,1]
	v_pk_mul_f32 v[200:201], v[116:117], v[92:93] op_sel:[0,1]
	v_pk_mul_f32 v[202:203], v[116:117], v[104:105] op_sel:[0,1]
	v_pk_mul_f32 v[116:117], v[116:117], v[108:109] op_sel:[0,1]
	s_waitcnt vmcnt(2)
	v_pk_fma_f32 v[30:31], v[122:123], v[30:31], v[168:169] op_sel_hi:[1,0,1]
	v_pk_fma_f32 v[40:41], v[122:123], v[40:41], v[170:171] op_sel_hi:[1,0,1]
	v_pk_fma_f32 v[48:49], v[122:123], v[48:49], v[172:173] op_sel_hi:[1,0,1]
	v_pk_fma_f32 v[56:57], v[122:123], v[56:57], v[174:175] op_sel_hi:[1,0,1]
	v_pk_fma_f32 v[64:65], v[122:123], v[64:65], v[176:177] op_sel_hi:[1,0,1]
	v_pk_fma_f32 v[72:73], v[122:123], v[72:73], v[178:179] op_sel_hi:[1,0,1]
	v_pk_fma_f32 v[80:81], v[122:123], v[80:81], v[180:181] op_sel_hi:[1,0,1]
	v_pk_fma_f32 v[88:89], v[122:123], v[88:89], v[182:183] op_sel_hi:[1,0,1]
	v_pk_fma_f32 v[96:97], v[122:123], v[96:97], v[184:185] op_sel_hi:[1,0,1]
	v_pk_fma_f32 v[100:101], v[122:123], v[100:101], v[114:115] op_sel_hi:[1,0,1]
	s_waitcnt vmcnt(0)
	v_pk_fma_f32 v[34:35], v[126:127], v[34:35], v[186:187] op_sel_hi:[1,0,1]
	v_pk_fma_f32 v[44:45], v[126:127], v[44:45], v[188:189] op_sel_hi:[1,0,1]
	v_pk_fma_f32 v[52:53], v[126:127], v[52:53], v[190:191] op_sel_hi:[1,0,1]
	v_pk_fma_f32 v[60:61], v[126:127], v[60:61], v[192:193] op_sel_hi:[1,0,1]
	v_pk_fma_f32 v[68:69], v[126:127], v[68:69], v[194:195] op_sel_hi:[1,0,1]
	v_pk_fma_f32 v[76:77], v[126:127], v[76:77], v[196:197] op_sel_hi:[1,0,1]
	v_pk_fma_f32 v[84:85], v[126:127], v[84:85], v[198:199] op_sel_hi:[1,0,1]
	v_pk_fma_f32 v[92:93], v[126:127], v[92:93], v[200:201] op_sel_hi:[1,0,1]
	v_pk_fma_f32 v[104:105], v[126:127], v[104:105], v[202:203] op_sel_hi:[1,0,1]
	v_pk_fma_f32 v[108:109], v[126:127], v[108:109], v[116:117] op_sel_hi:[1,0,1]
	v_pk_fma_f32 v[30:31], v[118:119], v[32:33], v[30:31] op_sel_hi:[1,0,1]
	v_pk_fma_f32 v[32:33], v[118:119], v[42:43], v[40:41] op_sel_hi:[1,0,1]
	v_pk_fma_f32 v[40:41], v[118:119], v[50:51], v[48:49] op_sel_hi:[1,0,1]
	v_pk_fma_f32 v[42:43], v[118:119], v[58:59], v[56:57] op_sel_hi:[1,0,1]
	v_pk_fma_f32 v[48:49], v[118:119], v[66:67], v[64:65] op_sel_hi:[1,0,1]
	v_pk_fma_f32 v[50:51], v[118:119], v[74:75], v[72:73] op_sel_hi:[1,0,1]
	v_pk_fma_f32 v[56:57], v[118:119], v[82:83], v[80:81] op_sel_hi:[1,0,1]
	v_pk_fma_f32 v[58:59], v[118:119], v[90:91], v[88:89] op_sel_hi:[1,0,1]
	v_pk_fma_f32 v[64:65], v[118:119], v[98:99], v[96:97] op_sel_hi:[1,0,1]
	v_pk_fma_f32 v[66:67], v[118:119], v[102:103], v[100:101] op_sel_hi:[1,0,1]
	v_pk_fma_f32 v[34:35], v[124:125], v[36:37], v[34:35] op_sel_hi:[1,0,1]
	v_pk_fma_f32 v[36:37], v[124:125], v[46:47], v[44:45] op_sel_hi:[1,0,1]
	v_pk_fma_f32 v[44:45], v[124:125], v[54:55], v[52:53] op_sel_hi:[1,0,1]
	v_pk_fma_f32 v[46:47], v[124:125], v[62:63], v[60:61] op_sel_hi:[1,0,1]
	v_pk_fma_f32 v[52:53], v[124:125], v[70:71], v[68:69] op_sel_hi:[1,0,1]
	v_pk_fma_f32 v[54:55], v[124:125], v[78:79], v[76:77] op_sel_hi:[1,0,1]
	v_pk_fma_f32 v[60:61], v[124:125], v[86:87], v[84:85] op_sel_hi:[1,0,1]
	v_pk_fma_f32 v[62:63], v[124:125], v[94:95], v[92:93] op_sel_hi:[1,0,1]
	v_pk_fma_f32 v[68:69], v[124:125], v[106:107], v[104:105] op_sel_hi:[1,0,1]
	v_pk_fma_f32 v[70:71], v[124:125], v[110:111], v[108:109] op_sel_hi:[1,0,1]
	v_pk_fma_f32 v[30:31], v[120:121], v[128:129], v[30:31] op_sel_hi:[1,0,1]
	v_pk_fma_f32 v[32:33], v[120:121], v[130:131], v[32:33] op_sel_hi:[1,0,1]
	v_pk_fma_f32 v[40:41], v[120:121], v[132:133], v[40:41] op_sel_hi:[1,0,1]
	v_pk_fma_f32 v[42:43], v[120:121], v[134:135], v[42:43] op_sel_hi:[1,0,1]
	v_pk_fma_f32 v[48:49], v[120:121], v[136:137], v[48:49] op_sel_hi:[1,0,1]
	v_pk_fma_f32 v[50:51], v[120:121], v[138:139], v[50:51] op_sel_hi:[1,0,1]
	v_pk_fma_f32 v[56:57], v[120:121], v[140:141], v[56:57] op_sel_hi:[1,0,1]
	v_pk_fma_f32 v[58:59], v[120:121], v[142:143], v[58:59] op_sel_hi:[1,0,1]
	v_pk_fma_f32 v[64:65], v[120:121], v[160:161], v[64:65] op_sel_hi:[1,0,1]
	v_pk_fma_f32 v[66:67], v[120:121], v[162:163], v[66:67] op_sel_hi:[1,0,1]
	v_pk_fma_f32 v[34:35], v[112:113], v[144:145], v[34:35] op_sel_hi:[1,0,1]
	v_pk_fma_f32 v[36:37], v[112:113], v[146:147], v[36:37] op_sel_hi:[1,0,1]
	v_pk_fma_f32 v[44:45], v[112:113], v[148:149], v[44:45] op_sel_hi:[1,0,1]
	v_pk_fma_f32 v[46:47], v[112:113], v[150:151], v[46:47] op_sel_hi:[1,0,1]
	v_pk_fma_f32 v[52:53], v[112:113], v[152:153], v[52:53] op_sel_hi:[1,0,1]
	v_pk_fma_f32 v[54:55], v[112:113], v[154:155], v[54:55] op_sel_hi:[1,0,1]
	v_pk_fma_f32 v[60:61], v[112:113], v[156:157], v[60:61] op_sel_hi:[1,0,1]
	v_pk_fma_f32 v[62:63], v[112:113], v[158:159], v[62:63] op_sel_hi:[1,0,1]
	v_pk_fma_f32 v[68:69], v[112:113], v[164:165], v[68:69] op_sel_hi:[1,0,1]
	v_pk_fma_f32 v[70:71], v[112:113], v[166:167], v[70:71] op_sel_hi:[1,0,1]
	v_pk_add_f32 v[10:11], v[10:11], v[30:31]
	v_pk_add_f32 v[14:15], v[14:15], v[32:33]
	v_pk_add_f32 v[12:13], v[12:13], v[40:41]
	v_pk_add_f32 v[18:19], v[18:19], v[42:43]
	v_pk_add_f32 v[16:17], v[16:17], v[48:49]
	v_pk_add_f32 v[22:23], v[22:23], v[50:51]
	v_pk_add_f32 v[20:21], v[20:21], v[56:57]
	v_pk_add_f32 v[26:27], v[26:27], v[58:59]
	v_pk_add_f32 v[24:25], v[24:25], v[64:65]
	v_pk_add_f32 v[28:29], v[28:29], v[66:67]
	v_pk_add_f32 v[10:11], v[10:11], v[34:35]
	v_pk_add_f32 v[14:15], v[14:15], v[36:37]
	v_pk_add_f32 v[12:13], v[12:13], v[44:45]
	v_pk_add_f32 v[18:19], v[18:19], v[46:47]
	v_pk_add_f32 v[16:17], v[16:17], v[52:53]
	v_pk_add_f32 v[22:23], v[22:23], v[54:55]
	v_pk_add_f32 v[20:21], v[20:21], v[60:61]
	v_pk_add_f32 v[26:27], v[26:27], v[62:63]
	v_pk_add_f32 v[24:25], v[24:25], v[68:69]
	v_pk_add_f32 v[28:29], v[28:29], v[70:71]
	s_cbranch_scc0 .LBB0_12
	s_mul_i32 s24, s22, 0x12000
	s_mul_hi_i32 s23, s22, 0x12000
	s_add_u32 s24, s10, s24
	s_addc_u32 s23, s11, s23
	s_add_u32 s24, s24, s6
	s_addc_u32 s25, s23, s7
	s_mul_hi_i32 s23, s22, 0xb4000
	s_mul_i32 s22, s22, 0xb4000
	s_add_u32 s6, s22, s6
	s_addc_u32 s7, s23, s7
	ds_write2st64_b64 v39, v[10:11], v[14:15] offset1:1
	ds_write2st64_b64 v39, v[12:13], v[18:19] offset0:2 offset1:3
	ds_write2st64_b64 v39, v[16:17], v[22:23] offset0:4 offset1:5
	ds_write2st64_b64 v39, v[20:21], v[26:27] offset0:6 offset1:7
	ds_write2st64_b64 v39, v[24:25], v[28:29] offset0:8 offset1:9
	v_lshl_add_u64 v[8:9], s[24:25], 0, v[2:3]
	v_lshl_add_u64 v[10:11], v[6:7], 0, s[6:7]
	s_mov_b64 s[6:7], 0
	v_mov_b32_e32 v12, v38
	v_mov_b32_e32 v13, v1
	s_waitcnt lgkmcnt(0)
	s_barrier

.LBB0_98:
	s_lshr_b32 s4, s4, 14
	s_ashr_i32 s18, s8, 12
	s_add_i32 s4, s4, 8
	s_and_b64 s[16:17], s[16:17], exec
	s_cselect_b32 s4, s18, s4
	s_mul_hi_i32 s17, s4, 0x12000
	s_mul_i32 s4, s4, 0x12000
	s_add_u32 s16, s20, s4
	s_addc_u32 s17, s21, s17
	v_lshl_add_u64 v[22:23], s[16:17], 0, v[4:5]
	v_add_co_u32_e32 v8, vcc, s25, v22
	v_lshl_add_u64 v[24:25], s[12:13], 0, v[4:5]
	s_nop 0
	v_addc_co_u32_e32 v9, vcc, 0, v23, vcc
	global_load_dwordx4 v[10:13], v[22:23], off
	global_load_dwordx4 v[14:17], v[8:9], off offset:-4096
	global_load_dwordx4 v[18:21], v[24:25], off nt
	s_lshl_b64 s[12:13], s[14:15], 12
	v_lshl_add_u64 v[6:7], v[2:3], 0, s[12:13]
	v_lshl_add_u64 v[26:27], v[22:23], 0, s[6:7]
	s_add_u32 s8, s8, s52
	s_addc_u32 s9, s9, s53
	s_add_u32 s0, s0, s2
	s_addc_u32 s1, s1, s3
	s_cmp_lt_i32 s8, 0x10000
	s_waitcnt vmcnt(0)
	v_pk_add_f32 v[16:17], v[16:17], 1.0 op_sel_hi:[1,0]
	v_pk_add_f32 v[14:15], v[14:15], 1.0 op_sel_hi:[1,0]
	v_pk_fma_f32 v[12:13], v[20:21], v[16:17], v[12:13]
	v_pk_fma_f32 v[10:11], v[18:19], v[14:15], v[10:11]
	v_bfe_u32 v16, v12, 16, 1
	v_bfe_u32 v14, v10, 16, 1
	v_bfe_u32 v15, v11, 16, 1
	v_bfe_u32 v17, v13, 16, 1
	v_add3_u32 v10, v10, v14, s22
	v_add3_u32 v12, v12, v16, s22
	v_add3_u32 v11, v11, v15, s22
	v_add3_u32 v13, v13, v17, s22
	v_lshrrev_b32_e32 v10, 16, v10
	v_lshrrev_b32_e32 v12, 16, v12
	v_and_or_b32 v10, v11, s23, v10
	v_and_or_b32 v11, v13, s23, v12
	global_store_dwordx2 v[6:7], v[10:11], off
	global_load_dwordx4 v[10:13], v[26:27], off offset:1024
	s_nop 0
	global_load_dwordx4 v[14:17], v[22:23], off offset:1024
	global_load_dwordx4 v[18:21], v[24:25], off offset:1024 nt
	s_waitcnt vmcnt(2)
	v_pk_add_f32 v[12:13], v[12:13], 1.0 op_sel_hi:[1,0]
	v_pk_add_f32 v[10:11], v[10:11], 1.0 op_sel_hi:[1,0]
	s_waitcnt vmcnt(0)
	v_pk_fma_f32 v[12:13], v[20:21], v[12:13], v[16:17]
	v_pk_fma_f32 v[10:11], v[18:19], v[10:11], v[14:15]
	v_bfe_u32 v16, v12, 16, 1
	v_bfe_u32 v14, v10, 16, 1
	v_bfe_u32 v15, v11, 16, 1
	v_bfe_u32 v17, v13, 16, 1
	v_add3_u32 v10, v10, v14, s22
	v_add3_u32 v12, v12, v16, s22
	v_add3_u32 v11, v11, v15, s22
	v_add3_u32 v13, v13, v17, s22
	v_lshrrev_b32_e32 v10, 16, v10
	v_lshrrev_b32_e32 v12, 16, v12
	v_and_or_b32 v10, v11, s23, v10
	v_and_or_b32 v11, v13, s23, v12
	global_store_dwordx2 v[6:7], v[10:11], off offset:512
	global_load_dwordx4 v[10:13], v[26:27], off offset:2048
	s_nop 0
	global_load_dwordx4 v[14:17], v[22:23], off offset:2048
	global_load_dwordx4 v[18:21], v[24:25], off offset:2048 nt
	s_waitcnt vmcnt(2)
	v_pk_add_f32 v[12:13], v[12:13], 1.0 op_sel_hi:[1,0]
	v_pk_add_f32 v[10:11], v[10:11], 1.0 op_sel_hi:[1,0]
	s_waitcnt vmcnt(0)
	v_pk_fma_f32 v[12:13], v[20:21], v[12:13], v[16:17]
	v_pk_fma_f32 v[10:11], v[18:19], v[10:11], v[14:15]
	v_bfe_u32 v16, v12, 16, 1
	v_bfe_u32 v14, v10, 16, 1
	v_bfe_u32 v15, v11, 16, 1
	v_bfe_u32 v17, v13, 16, 1
	v_add3_u32 v10, v10, v14, s22
	v_add3_u32 v12, v12, v16, s22
	v_add3_u32 v11, v11, v15, s22
	v_add3_u32 v13, v13, v17, s22
	v_lshrrev_b32_e32 v10, 16, v10
	v_lshrrev_b32_e32 v12, 16, v12
	v_and_or_b32 v10, v11, s23, v10
	v_and_or_b32 v11, v13, s23, v12
	global_store_dwordx2 v[6:7], v[10:11], off offset:1024
	global_load_dwordx4 v[10:13], v[26:27], off offset:3072
	s_nop 0
	global_load_dwordx4 v[14:17], v[22:23], off offset:3072
	global_load_dwordx4 v[18:21], v[24:25], off offset:3072 nt
	v_add_co_u32_e32 v22, vcc, s24, v22
	s_waitcnt vmcnt(2)
	v_pk_add_f32 v[12:13], v[12:13], 1.0 op_sel_hi:[1,0]
	v_pk_add_f32 v[10:11], v[10:11], 1.0 op_sel_hi:[1,0]
	s_waitcnt vmcnt(0)
	v_pk_fma_f32 v[12:13], v[20:21], v[12:13], v[16:17]
	v_pk_fma_f32 v[10:11], v[18:19], v[10:11], v[14:15]
	v_bfe_u32 v16, v12, 16, 1
	v_bfe_u32 v14, v10, 16, 1
	v_bfe_u32 v15, v11, 16, 1
	v_bfe_u32 v17, v13, 16, 1
	v_add3_u32 v10, v10, v14, s22
	v_add3_u32 v12, v12, v16, s22
	v_add3_u32 v11, v11, v15, s22
	v_add3_u32 v13, v13, v17, s22
	v_lshrrev_b32_e32 v10, 16, v10
	v_lshrrev_b32_e32 v12, 16, v12
	v_addc_co_u32_e32 v23, vcc, 0, v23, vcc
	v_and_or_b32 v10, v11, s23, v10
	v_and_or_b32 v11, v13, s23, v12
	global_store_dwordx2 v[6:7], v[10:11], off offset:1536
	v_add_co_u32_e32 v24, vcc, s24, v24
	global_load_dwordx4 v[10:13], v[22:23], off
	global_load_dwordx4 v[14:17], v[8:9], off
	v_addc_co_u32_e32 v25, vcc, 0, v25, vcc
	global_load_dwordx4 v[18:21], v[24:25], off nt
	s_waitcnt vmcnt(1)
	v_pk_add_f32 v[16:17], v[16:17], 1.0 op_sel_hi:[1,0]
	v_pk_add_f32 v[14:15], v[14:15], 1.0 op_sel_hi:[1,0]
	s_waitcnt vmcnt(0)
	v_pk_fma_f32 v[12:13], v[20:21], v[16:17], v[12:13]
	v_pk_fma_f32 v[10:11], v[18:19], v[14:15], v[10:11]
	v_bfe_u32 v16, v12, 16, 1
	v_bfe_u32 v14, v10, 16, 1
	v_bfe_u32 v15, v11, 16, 1
	v_bfe_u32 v17, v13, 16, 1
	v_add3_u32 v10, v10, v14, s22
	v_add3_u32 v12, v12, v16, s22
	v_add3_u32 v11, v11, v15, s22
	v_add3_u32 v13, v13, v17, s22
	v_lshrrev_b32_e32 v10, 16, v10
	v_lshrrev_b32_e32 v12, 16, v12
	v_and_or_b32 v10, v11, s23, v10
	v_and_or_b32 v11, v13, s23, v12
	global_store_dwordx2 v[6:7], v[10:11], off offset:2048
	global_load_dwordx4 v[10:13], v[8:9], off offset:1024
	s_nop 0
	global_load_dwordx4 v[14:17], v[22:23], off offset:1024
	global_load_dwordx4 v[18:21], v[24:25], off offset:1024 nt
	s_waitcnt vmcnt(2)
	v_pk_add_f32 v[12:13], v[12:13], 1.0 op_sel_hi:[1,0]
	v_pk_add_f32 v[10:11], v[10:11], 1.0 op_sel_hi:[1,0]
	s_waitcnt vmcnt(0)
	v_pk_fma_f32 v[12:13], v[20:21], v[12:13], v[16:17]
	v_pk_fma_f32 v[10:11], v[18:19], v[10:11], v[14:15]
	v_bfe_u32 v16, v12, 16, 1
	v_bfe_u32 v14, v10, 16, 1
	v_bfe_u32 v15, v11, 16, 1
	v_bfe_u32 v17, v13, 16, 1
	v_add3_u32 v10, v10, v14, s22
	v_add3_u32 v12, v12, v16, s22
	v_add3_u32 v11, v11, v15, s22
	v_add3_u32 v13, v13, v17, s22
	v_lshrrev_b32_e32 v10, 16, v10
	v_lshrrev_b32_e32 v12, 16, v12
	v_and_or_b32 v10, v11, s23, v10
	v_and_or_b32 v11, v13, s23, v12
	global_store_dwordx2 v[6:7], v[10:11], off offset:2560
	global_load_dwordx4 v[10:13], v[8:9], off offset:2048
	s_nop 0
	global_load_dwordx4 v[14:17], v[22:23], off offset:2048
	global_load_dwordx4 v[18:21], v[24:25], off offset:2048 nt
	s_waitcnt vmcnt(2)
	v_pk_add_f32 v[12:13], v[12:13], 1.0 op_sel_hi:[1,0]
	v_pk_add_f32 v[10:11], v[10:11], 1.0 op_sel_hi:[1,0]
	s_waitcnt vmcnt(0)
	v_pk_fma_f32 v[12:13], v[20:21], v[12:13], v[16:17]
	v_pk_fma_f32 v[10:11], v[18:19], v[10:11], v[14:15]
	v_bfe_u32 v16, v12, 16, 1
	v_bfe_u32 v14, v10, 16, 1
	v_bfe_u32 v15, v11, 16, 1
	v_bfe_u32 v17, v13, 16, 1
	v_add3_u32 v10, v10, v14, s22
	v_add3_u32 v12, v12, v16, s22
	v_add3_u32 v11, v11, v15, s22
	v_add3_u32 v13, v13, v17, s22
	v_lshrrev_b32_e32 v10, 16, v10
	v_lshrrev_b32_e32 v12, 16, v12
	v_and_or_b32 v10, v11, s23, v10
	v_and_or_b32 v11, v13, s23, v12
	global_store_dwordx2 v[6:7], v[10:11], off offset:3072
	global_load_dwordx4 v[10:13], v[8:9], off offset:3072
	s_nop 0
	global_load_dwordx4 v[14:17], v[22:23], off offset:3072
	global_load_dwordx4 v[18:21], v[24:25], off offset:3072 nt
	s_waitcnt vmcnt(2)
	v_pk_add_f32 v[8:9], v[12:13], 1.0 op_sel_hi:[1,0]
	v_pk_add_f32 v[10:11], v[10:11], 1.0 op_sel_hi:[1,0]
	s_waitcnt vmcnt(0)
	v_pk_fma_f32 v[8:9], v[20:21], v[8:9], v[16:17]
	v_pk_fma_f32 v[10:11], v[18:19], v[10:11], v[14:15]
	v_bfe_u32 v14, v8, 16, 1
	v_bfe_u32 v12, v10, 16, 1
	v_bfe_u32 v13, v11, 16, 1
	v_bfe_u32 v15, v9, 16, 1
	v_add3_u32 v10, v10, v12, s22
	v_add3_u32 v8, v8, v14, s22
	v_add3_u32 v11, v11, v13, s22
	v_add3_u32 v9, v9, v15, s22
	v_lshrrev_b32_e32 v10, 16, v10
	v_lshrrev_b32_e32 v12, 16, v8
	v_and_or_b32 v8, v11, s23, v10
	v_and_or_b32 v9, v9, s23, v12
	global_store_dwordx2 v[6:7], v[8:9], off offset:3584
	s_cbranch_scc0 .LBB0_103
